# v74 tail split + MoE table rebuild skipped in phases 10/11/19/20 + next-unit gather indices prefetched at unit start
# baseline (speedup 1.0000x reference)
.Lgpf_a:
	v_lshl_add_u64 v[202:203], v[2:3], 0, s[28:29]
	s_mov_b32 s51, -2
	v_mov_b32_e32 v180, v4
	v_mov_b32_e32 v1, v0
	v_mov_b32_e32 v2, v0
	v_mov_b32_e32 v3, v0
	v_mov_b32_e32 v8, v0
	v_mov_b32_e32 v9, v0
	v_mov_b32_e32 v10, v0
	v_mov_b32_e32 v11, v0
	v_mov_b32_e32 v16, v0
	v_mov_b32_e32 v17, v0
	v_mov_b32_e32 v18, v0
	v_mov_b32_e32 v19, v0
	v_mov_b32_e32 v24, v0
	v_mov_b32_e32 v25, v0
	v_mov_b32_e32 v26, v0
	v_mov_b32_e32 v27, v0
	v_mov_b32_e32 v32, v0
	v_mov_b32_e32 v33, v0
	v_mov_b32_e32 v34, v0
	v_mov_b32_e32 v35, v0
	v_mov_b32_e32 v40, v0
	v_mov_b32_e32 v41, v0
	v_mov_b32_e32 v42, v0
	v_mov_b32_e32 v43, v0
	v_mov_b32_e32 v48, v0
	v_mov_b32_e32 v49, v0
	v_mov_b32_e32 v50, v0
	v_mov_b32_e32 v51, v0
	v_mov_b32_e32 v56, v0
	v_mov_b32_e32 v57, v0
	v_mov_b32_e32 v58, v0
	v_mov_b32_e32 v59, v0
	v_mov_b32_e32 v4, v0
	v_mov_b32_e32 v5, v0
	v_mov_b32_e32 v6, v0
	v_mov_b32_e32 v7, v0
	v_mov_b32_e32 v12, v0
	v_mov_b32_e32 v13, v0
	v_mov_b32_e32 v14, v0
	v_mov_b32_e32 v15, v0
	v_mov_b32_e32 v20, v0
	v_mov_b32_e32 v21, v0
	v_mov_b32_e32 v22, v0
	v_mov_b32_e32 v23, v0
	v_mov_b32_e32 v28, v0
	v_mov_b32_e32 v29, v0
	v_mov_b32_e32 v30, v0
	v_mov_b32_e32 v31, v0
	v_mov_b32_e32 v36, v0
	v_mov_b32_e32 v37, v0
	v_mov_b32_e32 v38, v0
	v_mov_b32_e32 v39, v0
	v_mov_b32_e32 v44, v0
	v_mov_b32_e32 v45, v0
	v_mov_b32_e32 v46, v0
	v_mov_b32_e32 v47, v0
	v_mov_b32_e32 v52, v0
	v_mov_b32_e32 v53, v0
	v_mov_b32_e32 v54, v0
	v_mov_b32_e32 v55, v0
	v_mov_b32_e32 v60, v0
	v_mov_b32_e32 v61, v0
	v_mov_b32_e32 v62, v0
	v_mov_b32_e32 v63, v0
	v_mov_b32_e32 v64, v0
	v_mov_b32_e32 v65, v0
	v_mov_b32_e32 v66, v0
	v_mov_b32_e32 v67, v0
	v_mov_b32_e32 v72, v0
	v_mov_b32_e32 v73, v0
	v_mov_b32_e32 v74, v0
	v_mov_b32_e32 v75, v0
	v_mov_b32_e32 v80, v0
	v_mov_b32_e32 v81, v0
	v_mov_b32_e32 v82, v0
	v_mov_b32_e32 v83, v0
	v_mov_b32_e32 v88, v0
	v_mov_b32_e32 v89, v0
	v_mov_b32_e32 v90, v0
	v_mov_b32_e32 v91, v0
	v_mov_b32_e32 v96, v0
	v_mov_b32_e32 v97, v0
	v_mov_b32_e32 v98, v0
	v_mov_b32_e32 v99, v0
	v_mov_b32_e32 v104, v0
	v_mov_b32_e32 v105, v0
	v_mov_b32_e32 v106, v0
	v_mov_b32_e32 v107, v0
	v_mov_b32_e32 v112, v0
	v_mov_b32_e32 v113, v0
	v_mov_b32_e32 v114, v0
	v_mov_b32_e32 v115, v0
	v_mov_b32_e32 v120, v0
	v_mov_b32_e32 v121, v0
	v_mov_b32_e32 v122, v0
	v_mov_b32_e32 v123, v0
	v_mov_b32_e32 v68, v0
	v_mov_b32_e32 v69, v0
	v_mov_b32_e32 v70, v0
	v_mov_b32_e32 v71, v0
	v_mov_b32_e32 v76, v0
	v_mov_b32_e32 v77, v0
	v_mov_b32_e32 v78, v0
	v_mov_b32_e32 v79, v0
	v_mov_b32_e32 v84, v0
	v_mov_b32_e32 v85, v0
	v_mov_b32_e32 v86, v0
	v_mov_b32_e32 v87, v0
	v_mov_b32_e32 v92, v0
	v_mov_b32_e32 v93, v0
	v_mov_b32_e32 v94, v0
	v_mov_b32_e32 v95, v0
	v_mov_b32_e32 v100, v0
	v_mov_b32_e32 v101, v0
	v_mov_b32_e32 v102, v0
	v_mov_b32_e32 v103, v0
	v_mov_b32_e32 v108, v0
	v_mov_b32_e32 v109, v0
	v_mov_b32_e32 v110, v0
	v_mov_b32_e32 v111, v0
	v_mov_b32_e32 v116, v0
	v_mov_b32_e32 v117, v0
	v_mov_b32_e32 v118, v0
	v_mov_b32_e32 v119, v0
	v_mov_b32_e32 v124, v0
	v_mov_b32_e32 v125, v0
	v_mov_b32_e32 v126, v0
	v_mov_b32_e32 v127, v0
	s_cmp_eq_u32 s90, 3
	s_cbranch_scc1 .LBB0_1749
	s_cmp_eq_u32 s90, 1
	s_cbranch_scc1 .Lts_a0_h
	s_branch .Lts_a1_h
